# Fourier step 1 and step 2 loops: the 8 gather loads per pass issued back-to-back into separate registers with counted vmcnt waits (were load-wait-write serialized through one register tuple)
# speedup vs baseline: 1.0078x; 1.0077x over previous
; __device__ __forceinline__ int crow(int r, int hi) { return (r & 3) + 8 * (r >> 2) + 4 * hi; }
; __device__ __forceinline__ int v_st(int k, int c) { const int kk = (k & ~0xC) | ((k & 4) << 1) | ((k & 8) >> 1); return ((kk >> 3) * 4 + (c >> 5)) * 512 + ((kk & 7) * 32 + (c & 31)) * 2; }
; __device__ __forceinline__ unsigned f2bf(float f) { unsigned u = __builtin_bit_cast(unsigned, f); return (u + 0x7fffu + ((u >> 16) & 1u)) >> 16; }
; __device__ __forceinline__ void fourier_step2(Ctx& F, const bf16* Y, bf16* O) {
;     ...
;         for (int q = 0; q < 8; ++q) { const int idx = q * NTHR + tid, key = idx >> 5, c = (idx & 31) * 8;
;             const bf16x8 v = ld8(src + (size_t)key * 256 + c);
;             *(bf16x8*)(img + (c >> 7) * 32768 + (key >> 6) * 16384 + v_st(key & 63, c & 127)) = v; }
;         __syncthreads();
;         f32x16 acc0 = {}, acc1 = {};
;     ...
;         F2_S(0, 0, 0); F2_S(1, 0, 1); F2_S(2, 0, 2); F2_S(3, 0, 3); F2_S(4, 1, 0); F2_S(5, 1, 1); F2_S(6, 1, 2); F2_S(7, 1, 3);
;     ...
;         const int col = 512 + 32 * wave + r32;
; #pragma unroll
;         for (int r = 0; r < 16; ++r) { const int k2 = crow(r, hi);
;             O[(size_t)(b * SEQ + k1 + 128 * k2) * DM + col] = (bf16)f2bf(acc0[r] * scale);
;             O[(size_t)(b * SEQ + k1 + 128 * (k2 + 32)) * DM + col] = (bf16)f2bf(acc1[r] * scale); }
.LBB0_335:
	s_ashr_i32 s1, s0, 31
	s_lshl_b64 s[6:7], s[0:1], 15
	v_lshl_add_u64 v[126:127], v[96:97], 0, s[6:7]
	s_and_b32 s1, s5, 0x7f
	v_lshl_add_u64 v[0:1], v[126:127], 0, v[98:99]
	global_load_dwordx4 v[0:3], v[0:1], off
	v_lshl_add_u64 v[4:5], v[126:127], 0, v[100:101]
	global_load_dwordx4 v[4:7], v[4:5], off
	v_lshl_add_u64 v[8:9], v[126:127], 0, v[102:103]
	global_load_dwordx4 v[8:11], v[8:9], off
	v_lshl_add_u64 v[12:13], v[126:127], 0, v[104:105]
	global_load_dwordx4 v[12:15], v[12:13], off
	v_lshl_add_u64 v[16:17], v[126:127], 0, v[106:107]
	global_load_dwordx4 v[16:19], v[16:17], off
	v_lshl_add_u64 v[20:21], v[126:127], 0, v[108:109]
	global_load_dwordx4 v[20:23], v[20:21], off
	v_lshl_add_u64 v[24:25], v[126:127], 0, v[110:111]
	global_load_dwordx4 v[24:27], v[24:25], off
	v_lshl_add_u64 v[28:29], v[126:127], 0, v[112:113]
	global_load_dwordx4 v[28:31], v[28:29], off
	s_waitcnt vmcnt(7)
	ds_write_b128 v118, v[0:3]
	s_waitcnt vmcnt(6)
	ds_write_b128 v119, v[4:7]
	s_waitcnt vmcnt(5)
	ds_write_b128 v120, v[8:11]
	s_waitcnt vmcnt(4)
	ds_write_b128 v121, v[12:15]
	s_waitcnt vmcnt(3)
	ds_write_b128 v122, v[16:19]
	s_waitcnt vmcnt(2)
	ds_write_b128 v123, v[20:23]
	s_waitcnt vmcnt(1)
	ds_write_b128 v124, v[24:27]
	s_waitcnt vmcnt(0)
	ds_write_b128 v125, v[28:31]
	s_waitcnt lgkmcnt(0)
	s_barrier
	ds_read_b64_tr_b16 v[0:1], v116 offset:0
	ds_read_b64_tr_b16 v[2:3], v116 offset:0x800
	s_waitcnt lgkmcnt(0)
	ds_read_b64_tr_b16 v[126:127], v116 offset:0x1000
	ds_read_b64_tr_b16 v[128:129], v116 offset:0x1800
	s_waitcnt lgkmcnt(0)
	s_nop 0
	v_mfma_f32_32x32x16_bf16 v[16:31], v[92:95], v[0:3], 0
	v_mfma_f32_32x32x16_bf16 v[0:15], v[60:63], v[0:3], 0
	v_mfma_f32_32x32x16_bf16 v[16:31], v[88:91], v[126:129], v[16:31]
	v_mfma_f32_32x32x16_bf16 v[0:15], v[56:59], v[126:129], v[0:15]
	ds_read_b64_tr_b16 v[126:127], v116 offset:0x2000
	ds_read_b64_tr_b16 v[128:129], v116 offset:0x2800
	s_waitcnt lgkmcnt(0)
	s_nop 0
	v_mfma_f32_32x32x16_bf16 v[16:31], v[84:87], v[126:129], v[16:31]
	v_mfma_f32_32x32x16_bf16 v[0:15], v[52:55], v[126:129], v[0:15]
	ds_read_b64_tr_b16 v[126:127], v116 offset:0x3000
	ds_read_b64_tr_b16 v[128:129], v116 offset:0x3800
	s_waitcnt lgkmcnt(0)
	s_nop 0
	v_mfma_f32_32x32x16_bf16 v[16:31], v[80:83], v[126:129], v[16:31]
	v_mfma_f32_32x32x16_bf16 v[0:15], v[48:51], v[126:129], v[0:15]
	ds_read_b64_tr_b16 v[126:127], v116 offset:0x4000
	ds_read_b64_tr_b16 v[128:129], v116 offset:0x4800
	s_waitcnt lgkmcnt(0)
	s_nop 0
	v_mfma_f32_32x32x16_bf16 v[16:31], v[76:79], v[126:129], v[16:31]
	v_mfma_f32_32x32x16_bf16 v[0:15], v[44:47], v[126:129], v[0:15]
	ds_read_b64_tr_b16 v[126:127], v116 offset:0x5000
	ds_read_b64_tr_b16 v[128:129], v116 offset:0x5800
	s_waitcnt lgkmcnt(0)
	s_nop 0
	v_mfma_f32_32x32x16_bf16 v[16:31], v[72:75], v[126:129], v[16:31]
	v_mfma_f32_32x32x16_bf16 v[0:15], v[40:43], v[126:129], v[0:15]
	ds_read_b64_tr_b16 v[126:127], v116 offset:0x6000
	ds_read_b64_tr_b16 v[128:129], v116 offset:0x6800
	s_waitcnt lgkmcnt(0)
	s_nop 0
	v_mfma_f32_32x32x16_bf16 v[16:31], v[68:71], v[126:129], v[16:31]
	v_mfma_f32_32x32x16_bf16 v[0:15], v[36:39], v[126:129], v[0:15]
	ds_read_b64_tr_b16 v[126:127], v116 offset:0x7000
	ds_read_b64_tr_b16 v[128:129], v116 offset:0x7800
	s_waitcnt lgkmcnt(0)
	s_nop 0
	v_mfma_f32_32x32x16_bf16 v[16:31], v[64:67], v[126:129], v[16:31]
	s_and_b32 s6, s2, 0xffffe000
	s_or_b32 s1, s1, s6
	s_add_i32 s5, s5, s89
	s_add_i32 s2, s2, s3
	s_add_i32 s0, s0, s4
	s_cmpk_gt_i32 s5, 0x1ff
	s_nop 5
	v_mul_f32_e32 v16, 0x3ab504f3, v16
	v_mfma_f32_32x32x16_bf16 v[0:15], v[32:35], v[126:129], v[0:15]
	v_bfe_u32 v126, v16, 16, 1
	v_add3_u32 v16, v16, v126, s75
	v_or_b32_e32 v126, s1, v117
	v_ashrrev_i32_e32 v127, 31, v126
	v_lshlrev_b64 v[128:129], 11, v[126:127]
	v_lshl_add_u64 v[128:129], v[114:115], 0, v[128:129]
	global_store_short_d16_hi v[128:129], v16, off
	v_or_b32_e32 v128, 0x1000, v126
	s_nop 3
	v_mul_f32_e32 v0, 0x3ab504f3, v0
	v_ashrrev_i32_e32 v129, 31, v128
	v_bfe_u32 v16, v0, 16, 1
	v_lshlrev_b64 v[128:129], 11, v[128:129]
	v_add3_u32 v0, v0, v16, s75
	v_lshl_add_u64 v[128:129], v[114:115], 0, v[128:129]
	global_store_short_d16_hi v[128:129], v0, off
	v_mul_f32_e32 v0, 0x3ab504f3, v17
	v_bfe_u32 v16, v0, 16, 1
	v_add3_u32 v0, v0, v16, s75
	v_or_b32_e32 v16, 0x80, v126
	v_ashrrev_i32_e32 v17, 31, v16
	v_lshlrev_b64 v[16:17], 11, v[16:17]
	v_lshl_add_u64 v[16:17], v[114:115], 0, v[16:17]
	global_store_short_d16_hi v[16:17], v0, off
	v_mul_f32_e32 v0, 0x3ab504f3, v1
	v_bfe_u32 v1, v0, 16, 1
	v_add3_u32 v16, v0, v1, s75
	v_or_b32_e32 v0, 0x1080, v126
	v_ashrrev_i32_e32 v1, 31, v0
	v_lshlrev_b64 v[0:1], 11, v[0:1]
	v_lshl_add_u64 v[0:1], v[114:115], 0, v[0:1]
	global_store_short_d16_hi v[0:1], v16, off
	v_mul_f32_e32 v0, 0x3ab504f3, v18
	v_bfe_u32 v1, v0, 16, 1
	v_add3_u32 v16, v0, v1, s75
	v_or_b32_e32 v0, 0x100, v126
	v_ashrrev_i32_e32 v1, 31, v0
	v_lshlrev_b64 v[0:1], 11, v[0:1]
	v_lshl_add_u64 v[0:1], v[114:115], 0, v[0:1]
	global_store_short_d16_hi v[0:1], v16, off
	v_mul_f32_e32 v0, 0x3ab504f3, v2
	v_bfe_u32 v1, v0, 16, 1
	v_add3_u32 v2, v0, v1, s75
	v_or_b32_e32 v0, 0x1100, v126
	v_ashrrev_i32_e32 v1, 31, v0
	v_lshlrev_b64 v[0:1], 11, v[0:1]
	v_lshl_add_u64 v[0:1], v[114:115], 0, v[0:1]
	global_store_short_d16_hi v[0:1], v2, off
	v_mul_f32_e32 v0, 0x3ab504f3, v19
	v_bfe_u32 v1, v0, 16, 1
	v_add3_u32 v2, v0, v1, s75
	v_or_b32_e32 v0, 0x180, v126
	v_ashrrev_i32_e32 v1, 31, v0
	v_lshlrev_b64 v[0:1], 11, v[0:1]
	v_lshl_add_u64 v[0:1], v[114:115], 0, v[0:1]
	global_store_short_d16_hi v[0:1], v2, off
	v_mul_f32_e32 v0, 0x3ab504f3, v3
	v_bfe_u32 v1, v0, 16, 1
	v_add3_u32 v2, v0, v1, s75
	v_or_b32_e32 v0, 0x1180, v126
; __device__ __forceinline__ int crow(int r, int hi) { return (r & 3) + 8 * (r >> 2) + 4 * hi; }
; __device__ __forceinline__ unsigned f2bf(float f) { unsigned u = __builtin_bit_cast(unsigned, f); return (u + 0x7fffu + ((u >> 16) & 1u)) >> 16; }
; __device__ __forceinline__ void fourier_step2(Ctx& F, const bf16* Y, bf16* O) {
;     ...
; #pragma unroll
;         for (int r = 0; r < 16; ++r) { const int k2 = crow(r, hi);
;             O[(size_t)(b * SEQ + k1 + 128 * k2) * DM + col] = (bf16)f2bf(acc0[r] * scale);
;             O[(size_t)(b * SEQ + k1 + 128 * (k2 + 32)) * DM + col] = (bf16)f2bf(acc1[r] * scale); }
;         __syncthreads();
	v_ashrrev_i32_e32 v1, 31, v0
	v_lshlrev_b64 v[0:1], 11, v[0:1]
	v_lshl_add_u64 v[0:1], v[114:115], 0, v[0:1]
	global_store_short_d16_hi v[0:1], v2, off
	v_mul_f32_e32 v0, 0x3ab504f3, v20
	v_bfe_u32 v1, v0, 16, 1
	v_add3_u32 v2, v0, v1, s75
	v_or_b32_e32 v0, 0x400, v126
	v_ashrrev_i32_e32 v1, 31, v0
	v_lshlrev_b64 v[0:1], 11, v[0:1]
	v_lshl_add_u64 v[0:1], v[114:115], 0, v[0:1]
	global_store_short_d16_hi v[0:1], v2, off
	v_mul_f32_e32 v0, 0x3ab504f3, v4
	v_bfe_u32 v1, v0, 16, 1
	v_add3_u32 v2, v0, v1, s75
	v_or_b32_e32 v0, 0x1400, v126
	v_ashrrev_i32_e32 v1, 31, v0
	v_lshlrev_b64 v[0:1], 11, v[0:1]
	v_lshl_add_u64 v[0:1], v[114:115], 0, v[0:1]
	global_store_short_d16_hi v[0:1], v2, off
	v_mul_f32_e32 v0, 0x3ab504f3, v21
	v_bfe_u32 v1, v0, 16, 1
	v_add3_u32 v2, v0, v1, s75
	v_or_b32_e32 v0, 0x480, v126
	v_ashrrev_i32_e32 v1, 31, v0
	v_lshlrev_b64 v[0:1], 11, v[0:1]
	v_lshl_add_u64 v[0:1], v[114:115], 0, v[0:1]
	global_store_short_d16_hi v[0:1], v2, off
	v_mul_f32_e32 v0, 0x3ab504f3, v5
	v_bfe_u32 v1, v0, 16, 1
	v_add3_u32 v2, v0, v1, s75
	v_or_b32_e32 v0, 0x1480, v126
	v_ashrrev_i32_e32 v1, 31, v0
	v_lshlrev_b64 v[0:1], 11, v[0:1]
	v_lshl_add_u64 v[0:1], v[114:115], 0, v[0:1]
	global_store_short_d16_hi v[0:1], v2, off
	v_mul_f32_e32 v0, 0x3ab504f3, v22
	v_bfe_u32 v1, v0, 16, 1
	v_add3_u32 v2, v0, v1, s75
	v_or_b32_e32 v0, 0x500, v126
	v_ashrrev_i32_e32 v1, 31, v0
	v_lshlrev_b64 v[0:1], 11, v[0:1]
	v_lshl_add_u64 v[0:1], v[114:115], 0, v[0:1]
	global_store_short_d16_hi v[0:1], v2, off
	v_mul_f32_e32 v0, 0x3ab504f3, v6
	v_bfe_u32 v1, v0, 16, 1
	v_add3_u32 v2, v0, v1, s75
	v_or_b32_e32 v0, 0x1500, v126
	v_ashrrev_i32_e32 v1, 31, v0
	v_lshlrev_b64 v[0:1], 11, v[0:1]
	v_lshl_add_u64 v[0:1], v[114:115], 0, v[0:1]
	global_store_short_d16_hi v[0:1], v2, off
	v_mul_f32_e32 v0, 0x3ab504f3, v23
	v_bfe_u32 v1, v0, 16, 1
	v_add3_u32 v2, v0, v1, s75
	v_or_b32_e32 v0, 0x580, v126
	v_ashrrev_i32_e32 v1, 31, v0
	v_lshlrev_b64 v[0:1], 11, v[0:1]
	v_lshl_add_u64 v[0:1], v[114:115], 0, v[0:1]
	global_store_short_d16_hi v[0:1], v2, off
	v_mul_f32_e32 v0, 0x3ab504f3, v7
	v_bfe_u32 v1, v0, 16, 1
	v_add3_u32 v2, v0, v1, s75
	v_or_b32_e32 v0, 0x1580, v126
	v_ashrrev_i32_e32 v1, 31, v0
	v_lshlrev_b64 v[0:1], 11, v[0:1]
	v_lshl_add_u64 v[0:1], v[114:115], 0, v[0:1]
	global_store_short_d16_hi v[0:1], v2, off
	v_mul_f32_e32 v0, 0x3ab504f3, v24
	v_bfe_u32 v1, v0, 16, 1
	v_add3_u32 v2, v0, v1, s75
	v_or_b32_e32 v0, 0x800, v126
	v_ashrrev_i32_e32 v1, 31, v0
	v_lshlrev_b64 v[0:1], 11, v[0:1]
	v_lshl_add_u64 v[0:1], v[114:115], 0, v[0:1]
	global_store_short_d16_hi v[0:1], v2, off
	v_mul_f32_e32 v0, 0x3ab504f3, v8
	v_bfe_u32 v1, v0, 16, 1
	v_add3_u32 v2, v0, v1, s75
	v_or_b32_e32 v0, 0x1800, v126
	v_ashrrev_i32_e32 v1, 31, v0
	v_lshlrev_b64 v[0:1], 11, v[0:1]
	v_lshl_add_u64 v[0:1], v[114:115], 0, v[0:1]
	global_store_short_d16_hi v[0:1], v2, off
	v_mul_f32_e32 v0, 0x3ab504f3, v25
	v_bfe_u32 v1, v0, 16, 1
	v_add3_u32 v2, v0, v1, s75
	v_or_b32_e32 v0, 0x880, v126
	v_ashrrev_i32_e32 v1, 31, v0
	v_lshlrev_b64 v[0:1], 11, v[0:1]
	v_lshl_add_u64 v[0:1], v[114:115], 0, v[0:1]
	global_store_short_d16_hi v[0:1], v2, off
	v_mul_f32_e32 v0, 0x3ab504f3, v9
	v_bfe_u32 v1, v0, 16, 1
	v_add3_u32 v2, v0, v1, s75
	v_or_b32_e32 v0, 0x1880, v126
	v_ashrrev_i32_e32 v1, 31, v0
	v_lshlrev_b64 v[0:1], 11, v[0:1]
	v_lshl_add_u64 v[0:1], v[114:115], 0, v[0:1]
	global_store_short_d16_hi v[0:1], v2, off
	v_mul_f32_e32 v0, 0x3ab504f3, v26
	v_bfe_u32 v1, v0, 16, 1
	v_add3_u32 v2, v0, v1, s75
	v_or_b32_e32 v0, 0x900, v126
	v_ashrrev_i32_e32 v1, 31, v0
	v_lshlrev_b64 v[0:1], 11, v[0:1]
	v_lshl_add_u64 v[0:1], v[114:115], 0, v[0:1]
	global_store_short_d16_hi v[0:1], v2, off
	v_mul_f32_e32 v0, 0x3ab504f3, v10
	v_bfe_u32 v1, v0, 16, 1
	v_add3_u32 v2, v0, v1, s75
	v_or_b32_e32 v0, 0x1900, v126
	v_ashrrev_i32_e32 v1, 31, v0
	v_lshlrev_b64 v[0:1], 11, v[0:1]
	v_lshl_add_u64 v[0:1], v[114:115], 0, v[0:1]
	global_store_short_d16_hi v[0:1], v2, off
	v_mul_f32_e32 v0, 0x3ab504f3, v27
	v_bfe_u32 v1, v0, 16, 1
	v_add3_u32 v2, v0, v1, s75
	v_or_b32_e32 v0, 0x980, v126
	v_ashrrev_i32_e32 v1, 31, v0
	v_lshlrev_b64 v[0:1], 11, v[0:1]
	v_lshl_add_u64 v[0:1], v[114:115], 0, v[0:1]
	global_store_short_d16_hi v[0:1], v2, off
	v_mul_f32_e32 v0, 0x3ab504f3, v11
	v_bfe_u32 v1, v0, 16, 1
	v_add3_u32 v2, v0, v1, s75
	v_or_b32_e32 v0, 0x1980, v126
	v_ashrrev_i32_e32 v1, 31, v0
	v_lshlrev_b64 v[0:1], 11, v[0:1]
	v_lshl_add_u64 v[0:1], v[114:115], 0, v[0:1]
	global_store_short_d16_hi v[0:1], v2, off
	v_mul_f32_e32 v0, 0x3ab504f3, v28
	v_bfe_u32 v1, v0, 16, 1
	v_add3_u32 v2, v0, v1, s75
	v_or_b32_e32 v0, 0xc00, v126
	v_ashrrev_i32_e32 v1, 31, v0
	v_lshlrev_b64 v[0:1], 11, v[0:1]
	v_lshl_add_u64 v[0:1], v[114:115], 0, v[0:1]
	global_store_short_d16_hi v[0:1], v2, off
	v_mul_f32_e32 v0, 0x3ab504f3, v12
	v_bfe_u32 v1, v0, 16, 1
	v_add3_u32 v2, v0, v1, s75
	v_or_b32_e32 v0, 0x1c00, v126
	v_ashrrev_i32_e32 v1, 31, v0
	v_lshlrev_b64 v[0:1], 11, v[0:1]
	v_lshl_add_u64 v[0:1], v[114:115], 0, v[0:1]
	global_store_short_d16_hi v[0:1], v2, off
	v_mul_f32_e32 v0, 0x3ab504f3, v29
	v_bfe_u32 v1, v0, 16, 1
	v_add3_u32 v2, v0, v1, s75
	v_or_b32_e32 v0, 0xc80, v126
	v_ashrrev_i32_e32 v1, 31, v0
	v_lshlrev_b64 v[0:1], 11, v[0:1]
	v_lshl_add_u64 v[0:1], v[114:115], 0, v[0:1]
	global_store_short_d16_hi v[0:1], v2, off
	v_mul_f32_e32 v0, 0x3ab504f3, v13
	v_bfe_u32 v1, v0, 16, 1
	v_add3_u32 v2, v0, v1, s75
	v_or_b32_e32 v0, 0x1c80, v126
	v_ashrrev_i32_e32 v1, 31, v0
	v_lshlrev_b64 v[0:1], 11, v[0:1]
	v_lshl_add_u64 v[0:1], v[114:115], 0, v[0:1]
	global_store_short_d16_hi v[0:1], v2, off
	v_mul_f32_e32 v0, 0x3ab504f3, v30
	v_bfe_u32 v1, v0, 16, 1
	v_add3_u32 v2, v0, v1, s75
	v_or_b32_e32 v0, 0xd00, v126
	v_ashrrev_i32_e32 v1, 31, v0
	v_lshlrev_b64 v[0:1], 11, v[0:1]
	v_lshl_add_u64 v[0:1], v[114:115], 0, v[0:1]
	global_store_short_d16_hi v[0:1], v2, off
	v_mul_f32_e32 v0, 0x3ab504f3, v14
	v_bfe_u32 v1, v0, 16, 1
	v_add3_u32 v2, v0, v1, s75
	v_or_b32_e32 v0, 0x1d00, v126
	v_ashrrev_i32_e32 v1, 31, v0
	v_lshlrev_b64 v[0:1], 11, v[0:1]
	v_lshl_add_u64 v[0:1], v[114:115], 0, v[0:1]
	global_store_short_d16_hi v[0:1], v2, off
	v_mul_f32_e32 v0, 0x3ab504f3, v31
	v_bfe_u32 v1, v0, 16, 1
	v_add3_u32 v2, v0, v1, s75
	v_or_b32_e32 v0, 0xd80, v126
	v_ashrrev_i32_e32 v1, 31, v0
	v_lshlrev_b64 v[0:1], 11, v[0:1]
	v_lshl_add_u64 v[0:1], v[114:115], 0, v[0:1]
	global_store_short_d16_hi v[0:1], v2, off
	v_mul_f32_e32 v0, 0x3ab504f3, v15
	v_bfe_u32 v1, v0, 16, 1
	v_add3_u32 v2, v0, v1, s75
	v_or_b32_e32 v0, 0x1d80, v126
	v_ashrrev_i32_e32 v1, 31, v0
	v_lshlrev_b64 v[0:1], 11, v[0:1]
	v_lshl_add_u64 v[0:1], v[114:115], 0, v[0:1]
	global_store_short_d16_hi v[0:1], v2, off
	s_barrier
	s_cbranch_scc0 .LBB0_335

; __device__ __forceinline__ int v_st(int k, int c) { const int kk = (k & ~0xC) | ((k & 4) << 1) | ((k & 8) >> 1); return ((kk >> 3) * 4 + (c >> 5)) * 512 + ((kk & 7) * 32 + (c & 31)) * 2; }
; __device__ __forceinline__ void fourier_step1(Ctx& F, const bf16* P, bf16* Y) {
;     ...
;             for (int q = 0; q < 8; ++q) { const int idx = q * NTHR + tid, kb = idx >> 10, k = (idx >> 4) & 63, c = (idx & 15) * 8;
;                 const int part = kb >> 1, n1 = (kb & 1) * 64 + k;
;                 const bf16x8 v = ld8(P + (size_t)(b * SEQ + 64 * n1 + n2) * NP + (part ? PC_ZI : PC_ZR) + 128 * ch + c);
;                 *(bf16x8*)(img + kb * 16384 + v_st(k, c)) = v; }
;             __syncthreads();
.LBB0_510:
	s_lshl_b64 s[10:11], s[12:13], 1
	v_lshl_add_u64 v[130:131], v[98:99], 0, s[10:11]
	global_load_dwordx4 v[130:133], v[130:131], off
	v_lshl_add_u64 v[134:135], v[100:101], 0, s[10:11]
	global_load_dwordx4 v[134:137], v[134:135], off
	v_lshl_add_u64 v[138:139], v[102:103], 0, s[10:11]
	global_load_dwordx4 v[138:141], v[138:139], off
	v_lshl_add_u64 v[142:143], v[104:105], 0, s[10:11]
	global_load_dwordx4 v[142:145], v[142:143], off
	v_lshl_add_u64 v[146:147], v[106:107], 0, s[10:11]
	global_load_dwordx4 v[146:149], v[146:147], off
	v_lshl_add_u64 v[150:151], v[108:109], 0, s[10:11]
	global_load_dwordx4 v[150:153], v[150:151], off
	v_lshl_add_u64 v[154:155], v[110:111], 0, s[10:11]
	global_load_dwordx4 v[154:157], v[154:155], off
	v_lshl_add_u64 v[158:159], v[112:113], 0, s[10:11]
	global_load_dwordx4 v[158:161], v[158:159], off
	s_waitcnt vmcnt(7)
	ds_write_b128 v180, v[130:133]
	s_waitcnt vmcnt(6)
	ds_write_b128 v181, v[134:137]
	s_waitcnt vmcnt(5)
	ds_write_b128 v182, v[138:141]
	s_waitcnt vmcnt(4)
	ds_write_b128 v183, v[142:145]
	s_waitcnt vmcnt(3)
	ds_write_b128 v184, v[146:149]
	s_waitcnt vmcnt(2)
	ds_write_b128 v185, v[150:153]
	s_waitcnt vmcnt(1)
	ds_write_b128 v186, v[154:157]
	s_waitcnt vmcnt(0)
	ds_write_b128 v187, v[158:161]
	s_waitcnt lgkmcnt(0)
	s_barrier
	ds_read_b64_tr_b16 v[0:1], v162 offset:0
	ds_read_b64_tr_b16 v[2:3], v162 offset:0x800
	ds_read_b64_tr_b16 v[130:131], v162 offset:0x1000
	ds_read_b64_tr_b16 v[132:133], v162 offset:0x1800
	ds_read_b64_tr_b16 v[134:135], v162 offset:0x2000
	ds_read_b64_tr_b16 v[136:137], v162 offset:0x2800
	ds_read_b64_tr_b16 v[138:139], v162 offset:0x3000
	ds_read_b64_tr_b16 v[140:141], v162 offset:0x3800
	s_waitcnt lgkmcnt(0)
	s_nop 0
	v_mfma_f32_32x32x16_bf16 v[0:15], v[76:79], v[0:3], 0
	v_mfma_f32_32x32x16_bf16 v[0:15], v[72:75], v[130:133], v[0:15]
	ds_read_b64_tr_b16 v[130:131], v162 offset:0x4000
	ds_read_b64_tr_b16 v[132:133], v162 offset:0x4800
	v_mfma_f32_32x32x16_bf16 v[0:15], v[68:71], v[134:137], v[0:15]
	ds_read_b64_tr_b16 v[134:135], v162 offset:0x5000
	ds_read_b64_tr_b16 v[136:137], v162 offset:0x5800
	v_mfma_f32_32x32x16_bf16 v[0:15], v[64:67], v[138:141], v[0:15]
	ds_read_b64_tr_b16 v[138:139], v162 offset:0x6000
	ds_read_b64_tr_b16 v[140:141], v162 offset:0x6800
	ds_read_b64_tr_b16 v[142:143], v162 offset:0x7000
	ds_read_b64_tr_b16 v[144:145], v162 offset:0x7800
	s_waitcnt lgkmcnt(0)
	v_mfma_f32_32x32x16_bf16 v[0:15], v[60:63], v[130:133], v[0:15]
	ds_read_b64_tr_b16 v[130:131], v162 offset:0x8000
	ds_read_b64_tr_b16 v[132:133], v162 offset:0x8800
	v_mfma_f32_32x32x16_bf16 v[0:15], v[56:59], v[134:137], v[0:15]
	ds_read_b64_tr_b16 v[134:135], v162 offset:0x9000
	ds_read_b64_tr_b16 v[136:137], v162 offset:0x9800
	v_mfma_f32_32x32x16_bf16 v[0:15], v[52:55], v[138:141], v[0:15]
	ds_read_b64_tr_b16 v[138:139], v162 offset:0xa000
	ds_read_b64_tr_b16 v[140:141], v162 offset:0xa800
	v_mfma_f32_32x32x16_bf16 v[0:15], v[48:51], v[142:145], v[0:15]
	ds_read_b64_tr_b16 v[142:143], v162 offset:0xb000
	ds_read_b64_tr_b16 v[144:145], v162 offset:0xb800
	s_waitcnt lgkmcnt(0)
	v_mfma_f32_32x32x16_bf16 v[0:15], v[44:47], v[130:133], v[0:15]
	ds_read_b64_tr_b16 v[130:131], v162 offset:0xc000
	ds_read_b64_tr_b16 v[132:133], v162 offset:0xc800
	v_mfma_f32_32x32x16_bf16 v[0:15], v[40:43], v[134:137], v[0:15]
	ds_read_b64_tr_b16 v[134:135], v162 offset:0xd000
	ds_read_b64_tr_b16 v[136:137], v162 offset:0xd800
	v_mfma_f32_32x32x16_bf16 v[0:15], v[36:39], v[138:141], v[0:15]
	ds_read_b64_tr_b16 v[138:139], v162 offset:0xe000
	ds_read_b64_tr_b16 v[140:141], v162 offset:0xe800
	v_mfma_f32_32x32x16_bf16 v[0:15], v[32:35], v[142:145], v[0:15]
	ds_read_b64_tr_b16 v[142:143], v162 offset:0xf000
	ds_read_b64_tr_b16 v[144:145], v162 offset:0xf800
	s_waitcnt lgkmcnt(0)
	v_mfma_f32_32x32x16_bf16 v[0:15], v[28:31], v[130:133], v[0:15]
	v_or_b32_e32 v204, s12, v81
	v_lshl_add_u64 v[158:159], v[204:205], 1, s[2:3]
	v_lshl_add_u64 v[130:131], v[158:159], 0, v[114:115]
	v_add_co_u32_e32 v132, vcc, s97, v130
	v_lshl_add_u64 v[146:147], v[158:159], 0, v[122:123]
	s_nop 0
	v_addc_co_u32_e32 v133, vcc, 0, v131, vcc
	v_mfma_f32_32x32x16_bf16 v[0:15], v[24:27], v[134:137], v[0:15]
	v_lshl_add_u64 v[134:135], v[158:159], 0, v[116:117]
	v_lshl_add_u64 v[136:137], v[158:159], 0, v[118:119]
	v_lshl_add_u64 v[150:151], v[158:159], 0, v[124:125]
	v_lshl_add_u64 v[154:155], v[158:159], 0, v[126:127]
	v_mfma_f32_32x32x16_bf16 v[0:15], v[20:23], v[138:141], v[0:15]
	v_add_co_u32_e32 v138, vcc, s97, v134
	s_nop 1
	v_addc_co_u32_e32 v139, vcc, 0, v135, vcc
	v_mfma_f32_32x32x16_bf16 v[0:15], v[16:19], v[142:145], v[0:15]
	s_nop 11
	v_mul_f32_e32 v140, v189, v8
	v_mul_f32_e32 v8, v188, v8
	v_mul_f32_e32 v141, v191, v9
	v_mul_f32_e32 v9, v190, v9
	v_fma_f32 v140, v188, v0, -v140
	v_fmac_f32_e32 v8, v189, v0
	v_fma_f32 v0, v190, v1, -v141
	v_fmac_f32_e32 v9, v191, v1
	v_bfe_u32 v1, v140, 16, 1
	v_bfe_u32 v142, v0, 16, 1
	v_bfe_u32 v141, v8, 16, 1
	v_bfe_u32 v143, v9, 16, 1
	v_add3_u32 v1, v140, v1, s75
	v_add3_u32 v0, v0, v142, s75
	v_add3_u32 v8, v8, v141, s75
	v_add3_u32 v9, v9, v143, s75
	global_store_short_d16_hi v[130:131], v1, off
	global_store_short_d16_hi v[132:133], v8, off
	global_store_short_d16_hi v[134:135], v0, off
	global_store_short_d16_hi v[138:139], v9, off
	v_mul_f32_e32 v0, v193, v10
	v_fma_f32 v0, v192, v2, -v0
	v_bfe_u32 v1, v0, 16, 1
	v_add3_u32 v0, v0, v1, s75
	global_store_short_d16_hi v[136:137], v0, off
	v_mul_f32_e32 v0, v192, v10
	v_fmac_f32_e32 v0, v193, v2
	v_bfe_u32 v1, v0, 16, 1
	v_add_co_u32_e32 v140, vcc, s97, v136
	v_add3_u32 v0, v0, v1, s75
	s_nop 0
	v_addc_co_u32_e32 v141, vcc, 0, v137, vcc
	global_store_short_d16_hi v[140:141], v0, off
	v_mul_f32_e32 v0, v195, v11
	v_fma_f32 v0, v194, v3, -v0
	v_bfe_u32 v1, v0, 16, 1
	v_lshl_add_u64 v[142:143], v[158:159], 0, v[120:121]
	v_add3_u32 v0, v0, v1, s75
	global_store_short_d16_hi v[142:143], v0, off
	v_mul_f32_e32 v0, v194, v11
	v_fmac_f32_e32 v0, v195, v3
	v_bfe_u32 v1, v0, 16, 1
	v_add_co_u32_e32 v144, vcc, s97, v142
	v_add3_u32 v0, v0, v1, s75
	s_nop 0
	v_addc_co_u32_e32 v145, vcc, 0, v143, vcc
	global_store_short_d16_hi v[144:145], v0, off
	v_mul_f32_e32 v0, v197, v12
	v_fma_f32 v0, v196, v4, -v0
	v_bfe_u32 v1, v0, 16, 1
	v_add3_u32 v0, v0, v1, s75
	global_store_short_d16_hi v[146:147], v0, off
	v_mul_f32_e32 v0, v196, v12
	v_fmac_f32_e32 v0, v197, v4
	v_bfe_u32 v1, v0, 16, 1
	v_add_co_u32_e32 v148, vcc, s97, v146
	v_add3_u32 v0, v0, v1, s75
	s_nop 0
	v_addc_co_u32_e32 v149, vcc, 0, v147, vcc
	global_store_short_d16_hi v[148:149], v0, off
	v_mul_f32_e32 v0, v199, v13
	v_fma_f32 v0, v198, v5, -v0
	v_bfe_u32 v1, v0, 16, 1
	v_add3_u32 v0, v0, v1, s75
	global_store_short_d16_hi v[150:151], v0, off
	v_mul_f32_e32 v0, v198, v13
	v_fmac_f32_e32 v0, v199, v5
	v_bfe_u32 v1, v0, 16, 1
	v_add_co_u32_e32 v152, vcc, s97, v150
	v_add3_u32 v0, v0, v1, s75
	s_nop 0
	v_addc_co_u32_e32 v153, vcc, 0, v151, vcc
	global_store_short_d16_hi v[152:153], v0, off
	v_mul_f32_e32 v0, v201, v14
	v_fma_f32 v0, v200, v6, -v0
	v_bfe_u32 v1, v0, 16, 1
	v_add3_u32 v0, v0, v1, s75
	global_store_short_d16_hi v[154:155], v0, off
	v_mul_f32_e32 v0, v200, v14
	v_fmac_f32_e32 v0, v201, v6
	v_bfe_u32 v1, v0, 16, 1
	v_add_co_u32_e32 v156, vcc, s97, v154
	v_add3_u32 v0, v0, v1, s75
	s_nop 0
	v_addc_co_u32_e32 v157, vcc, 0, v155, vcc
	global_store_short_d16_hi v[156:157], v0, off
	v_mul_f32_e32 v0, v203, v15
	v_fma_f32 v0, v202, v7, -v0
	v_bfe_u32 v1, v0, 16, 1
	v_lshl_add_u64 v[158:159], v[158:159], 0, v[128:129]
	v_add3_u32 v0, v0, v1, s75
	global_store_short_d16_hi v[158:159], v0, off
	v_mul_f32_e32 v0, v202, v15
	v_fmac_f32_e32 v0, v203, v7
	v_bfe_u32 v1, v0, 16, 1
	v_add_co_u32_e32 v160, vcc, s97, v158
	v_add3_u32 v0, v0, v1, s75
	s_nop 0
	v_addc_co_u32_e32 v161, vcc, 0, v159, vcc
	global_store_short_d16_hi v[160:161], v0, off
	ds_read_b64_tr_b16 v[0:1], v162 offset:0x200
	ds_read_b64_tr_b16 v[2:3], v162 offset:0xa00
	ds_read_b64_tr_b16 v[210:211], v162 offset:0x1200
	ds_read_b64_tr_b16 v[212:213], v162 offset:0x1a00
	ds_read_b64_tr_b16 v[214:215], v162 offset:0x2200
	ds_read_b64_tr_b16 v[216:217], v162 offset:0x2a00
	ds_read_b64_tr_b16 v[218:219], v162 offset:0x3200
	ds_read_b64_tr_b16 v[220:221], v162 offset:0x3a00
	s_waitcnt lgkmcnt(0)
	s_nop 0
	v_mfma_f32_32x32x16_bf16 v[0:15], v[76:79], v[0:3], 0
	v_mfma_f32_32x32x16_bf16 v[0:15], v[72:75], v[210:213], v[0:15]
	ds_read_b64_tr_b16 v[210:211], v162 offset:0x4200
	ds_read_b64_tr_b16 v[212:213], v162 offset:0x4a00
	v_mfma_f32_32x32x16_bf16 v[0:15], v[68:71], v[214:217], v[0:15]
	ds_read_b64_tr_b16 v[214:215], v162 offset:0x5200
	ds_read_b64_tr_b16 v[216:217], v162 offset:0x5a00
	v_mfma_f32_32x32x16_bf16 v[0:15], v[64:67], v[218:221], v[0:15]
	ds_read_b64_tr_b16 v[218:219], v162 offset:0x6200
	ds_read_b64_tr_b16 v[220:221], v162 offset:0x6a00
	ds_read_b64_tr_b16 v[222:223], v162 offset:0x7200
	ds_read_b64_tr_b16 v[224:225], v162 offset:0x7a00
	s_waitcnt lgkmcnt(0)
	v_mfma_f32_32x32x16_bf16 v[0:15], v[60:63], v[210:213], v[0:15]
	ds_read_b64_tr_b16 v[210:211], v162 offset:0x8200
	ds_read_b64_tr_b16 v[212:213], v162 offset:0x8a00
	v_mfma_f32_32x32x16_bf16 v[0:15], v[56:59], v[214:217], v[0:15]
	ds_read_b64_tr_b16 v[214:215], v162 offset:0x9200
	ds_read_b64_tr_b16 v[216:217], v162 offset:0x9a00
	v_mfma_f32_32x32x16_bf16 v[0:15], v[52:55], v[218:221], v[0:15]
	ds_read_b64_tr_b16 v[218:219], v162 offset:0xa200
	ds_read_b64_tr_b16 v[220:221], v162 offset:0xaa00
	v_mfma_f32_32x32x16_bf16 v[0:15], v[48:51], v[222:225], v[0:15]
	ds_read_b64_tr_b16 v[222:223], v162 offset:0xb200
	ds_read_b64_tr_b16 v[224:225], v162 offset:0xba00
	s_waitcnt lgkmcnt(0)
	v_mfma_f32_32x32x16_bf16 v[0:15], v[44:47], v[210:213], v[0:15]
	ds_read_b64_tr_b16 v[210:211], v162 offset:0xc200
	ds_read_b64_tr_b16 v[212:213], v162 offset:0xca00
	v_mfma_f32_32x32x16_bf16 v[0:15], v[40:43], v[214:217], v[0:15]
	ds_read_b64_tr_b16 v[214:215], v162 offset:0xd200
	ds_read_b64_tr_b16 v[216:217], v162 offset:0xda00
	v_mfma_f32_32x32x16_bf16 v[0:15], v[36:39], v[218:221], v[0:15]
	ds_read_b64_tr_b16 v[218:219], v162 offset:0xe200
	ds_read_b64_tr_b16 v[220:221], v162 offset:0xea00
	v_mfma_f32_32x32x16_bf16 v[0:15], v[32:35], v[222:225], v[0:15]
	ds_read_b64_tr_b16 v[222:223], v162 offset:0xf200
	ds_read_b64_tr_b16 v[224:225], v162 offset:0xfa00
	s_waitcnt lgkmcnt(0)
	v_mfma_f32_32x32x16_bf16 v[0:15], v[28:31], v[210:213], v[0:15]
	v_mfma_f32_32x32x16_bf16 v[0:15], v[24:27], v[214:217], v[0:15]
	v_mfma_f32_32x32x16_bf16 v[0:15], v[20:23], v[218:221], v[0:15]
	v_mfma_f32_32x32x16_bf16 v[0:15], v[16:19], v[222:225], v[0:15]
	s_nop 11
	v_mul_f32_e32 v204, v189, v8
	v_mul_f32_e32 v8, v188, v8
	v_mul_f32_e32 v210, v191, v9
	v_mul_f32_e32 v9, v190, v9
	v_mul_f32_e32 v211, v193, v10
	v_mul_f32_e32 v10, v192, v10
	v_mul_f32_e32 v212, v195, v11
	v_fma_f32 v204, v188, v0, -v204
	v_fmac_f32_e32 v8, v189, v0
	v_fma_f32 v0, v190, v1, -v210
	v_fmac_f32_e32 v9, v191, v1
	v_fma_f32 v1, v192, v2, -v211
	v_fmac_f32_e32 v10, v193, v2
	v_fma_f32 v2, v194, v3, -v212
	v_bfe_u32 v210, v204, 16, 1
	v_bfe_u32 v212, v0, 16, 1
	v_bfe_u32 v211, v8, 16, 1
	v_bfe_u32 v213, v9, 16, 1
	v_bfe_u32 v214, v1, 16, 1
	v_bfe_u32 v215, v10, 16, 1
	v_bfe_u32 v216, v2, 16, 1
	v_add3_u32 v204, v204, v210, s75
	v_add3_u32 v0, v0, v212, s75
	v_add3_u32 v8, v8, v211, s75
	v_add3_u32 v9, v9, v213, s75
	v_add3_u32 v1, v1, v214, s75
	v_add3_u32 v10, v10, v215, s75
	global_store_short_d16_hi v[130:131], v204, off offset:64
	global_store_short_d16_hi v[132:133], v8, off offset:64
	global_store_short_d16_hi v[134:135], v0, off offset:64
	global_store_short_d16_hi v[138:139], v9, off offset:64
	global_store_short_d16_hi v[136:137], v1, off offset:64
	global_store_short_d16_hi v[140:141], v10, off offset:64
	v_add3_u32 v0, v2, v216, s75
	global_store_short_d16_hi v[142:143], v0, off offset:64
	v_mul_f32_e32 v0, v194, v11
	v_fmac_f32_e32 v0, v195, v3
	v_bfe_u32 v1, v0, 16, 1
	v_add3_u32 v0, v0, v1, s75
	global_store_short_d16_hi v[144:145], v0, off offset:64
	v_mul_f32_e32 v0, v197, v12
	v_fma_f32 v0, v196, v4, -v0
	v_bfe_u32 v1, v0, 16, 1
	v_add3_u32 v0, v0, v1, s75
	global_store_short_d16_hi v[146:147], v0, off offset:64
	v_mul_f32_e32 v0, v196, v12
	v_fmac_f32_e32 v0, v197, v4
	v_bfe_u32 v1, v0, 16, 1
	v_add3_u32 v0, v0, v1, s75
	global_store_short_d16_hi v[148:149], v0, off offset:64
	v_mul_f32_e32 v0, v199, v13
	v_fma_f32 v0, v198, v5, -v0
	v_bfe_u32 v1, v0, 16, 1
	v_add3_u32 v0, v0, v1, s75
	global_store_short_d16_hi v[150:151], v0, off offset:64
	v_mul_f32_e32 v0, v198, v13
	v_fmac_f32_e32 v0, v199, v5
	v_bfe_u32 v1, v0, 16, 1
	v_add3_u32 v0, v0, v1, s75
	global_store_short_d16_hi v[152:153], v0, off offset:64
	v_mul_f32_e32 v0, v201, v14
	v_fma_f32 v0, v200, v6, -v0
	v_bfe_u32 v1, v0, 16, 1
	v_add3_u32 v0, v0, v1, s75
	global_store_short_d16_hi v[154:155], v0, off offset:64
	v_mul_f32_e32 v0, v200, v14
	v_fmac_f32_e32 v0, v201, v6
	v_bfe_u32 v1, v0, 16, 1
	v_add3_u32 v0, v0, v1, s75
	global_store_short_d16_hi v[156:157], v0, off offset:64
	v_mul_f32_e32 v0, v203, v15
	v_fma_f32 v0, v202, v7, -v0
	v_bfe_u32 v1, v0, 16, 1
	v_add3_u32 v0, v0, v1, s75
	global_store_short_d16_hi v[158:159], v0, off offset:64
	v_mul_f32_e32 v0, v202, v15
	v_fmac_f32_e32 v0, v203, v7
	v_bfe_u32 v1, v0, 16, 1
	v_add3_u32 v0, v0, v1, s75
	global_store_short_d16_hi v[160:161], v0, off offset:64
	ds_read_b64_tr_b16 v[0:1], v162 offset:0x400
	ds_read_b64_tr_b16 v[2:3], v162 offset:0xc00
	ds_read_b64_tr_b16 v[210:211], v162 offset:0x1400
	ds_read_b64_tr_b16 v[212:213], v162 offset:0x1c00
	ds_read_b64_tr_b16 v[214:215], v162 offset:0x2400
	ds_read_b64_tr_b16 v[216:217], v162 offset:0x2c00
	ds_read_b64_tr_b16 v[218:219], v162 offset:0x3400
	ds_read_b64_tr_b16 v[220:221], v162 offset:0x3c00
	s_waitcnt lgkmcnt(0)
	s_nop 0
	v_mfma_f32_32x32x16_bf16 v[0:15], v[76:79], v[0:3], 0
	v_mfma_f32_32x32x16_bf16 v[0:15], v[72:75], v[210:213], v[0:15]
	ds_read_b64_tr_b16 v[210:211], v162 offset:0x4400
	ds_read_b64_tr_b16 v[212:213], v162 offset:0x4c00
	v_mfma_f32_32x32x16_bf16 v[0:15], v[68:71], v[214:217], v[0:15]
	ds_read_b64_tr_b16 v[214:215], v162 offset:0x5400
	ds_read_b64_tr_b16 v[216:217], v162 offset:0x5c00
	v_mfma_f32_32x32x16_bf16 v[0:15], v[64:67], v[218:221], v[0:15]
	ds_read_b64_tr_b16 v[218:219], v162 offset:0x6400
	ds_read_b64_tr_b16 v[220:221], v162 offset:0x6c00
	ds_read_b64_tr_b16 v[222:223], v162 offset:0x7400
	ds_read_b64_tr_b16 v[224:225], v162 offset:0x7c00
	s_waitcnt lgkmcnt(0)
	v_mfma_f32_32x32x16_bf16 v[0:15], v[60:63], v[210:213], v[0:15]
	ds_read_b64_tr_b16 v[210:211], v162 offset:0x8400
	ds_read_b64_tr_b16 v[212:213], v162 offset:0x8c00
	v_mfma_f32_32x32x16_bf16 v[0:15], v[56:59], v[214:217], v[0:15]
	ds_read_b64_tr_b16 v[214:215], v162 offset:0x9400
	ds_read_b64_tr_b16 v[216:217], v162 offset:0x9c00
	v_mfma_f32_32x32x16_bf16 v[0:15], v[52:55], v[218:221], v[0:15]
	ds_read_b64_tr_b16 v[218:219], v162 offset:0xa400
	ds_read_b64_tr_b16 v[220:221], v162 offset:0xac00
	v_mfma_f32_32x32x16_bf16 v[0:15], v[48:51], v[222:225], v[0:15]
	ds_read_b64_tr_b16 v[222:223], v162 offset:0xb400
	ds_read_b64_tr_b16 v[224:225], v162 offset:0xbc00
	s_waitcnt lgkmcnt(0)
	v_mfma_f32_32x32x16_bf16 v[0:15], v[44:47], v[210:213], v[0:15]
	ds_read_b64_tr_b16 v[210:211], v162 offset:0xc400
	ds_read_b64_tr_b16 v[212:213], v162 offset:0xcc00
	v_mfma_f32_32x32x16_bf16 v[0:15], v[40:43], v[214:217], v[0:15]
	ds_read_b64_tr_b16 v[214:215], v162 offset:0xd400
	ds_read_b64_tr_b16 v[216:217], v162 offset:0xdc00
	v_mfma_f32_32x32x16_bf16 v[0:15], v[36:39], v[218:221], v[0:15]
	ds_read_b64_tr_b16 v[218:219], v162 offset:0xe400
	ds_read_b64_tr_b16 v[220:221], v162 offset:0xec00
	v_mfma_f32_32x32x16_bf16 v[0:15], v[32:35], v[222:225], v[0:15]
	ds_read_b64_tr_b16 v[222:223], v162 offset:0xf400
	ds_read_b64_tr_b16 v[224:225], v162 offset:0xfc00
	s_waitcnt lgkmcnt(0)
	v_mfma_f32_32x32x16_bf16 v[0:15], v[28:31], v[210:213], v[0:15]
	v_mfma_f32_32x32x16_bf16 v[0:15], v[24:27], v[214:217], v[0:15]
	v_mfma_f32_32x32x16_bf16 v[0:15], v[20:23], v[218:221], v[0:15]
	v_mfma_f32_32x32x16_bf16 v[0:15], v[16:19], v[222:225], v[0:15]
	s_nop 11
	v_mul_f32_e32 v204, v189, v8
	v_mul_f32_e32 v8, v188, v8
	v_mul_f32_e32 v210, v191, v9
	v_mul_f32_e32 v9, v190, v9
	v_mul_f32_e32 v211, v193, v10
	v_mul_f32_e32 v10, v192, v10
	v_mul_f32_e32 v212, v195, v11
	v_fma_f32 v204, v188, v0, -v204
	v_fmac_f32_e32 v8, v189, v0
	v_fma_f32 v0, v190, v1, -v210
	v_fmac_f32_e32 v9, v191, v1
	v_fma_f32 v1, v192, v2, -v211
	v_fmac_f32_e32 v10, v193, v2
	v_fma_f32 v2, v194, v3, -v212
	v_bfe_u32 v210, v204, 16, 1
	v_bfe_u32 v212, v0, 16, 1
	v_bfe_u32 v211, v8, 16, 1
	v_bfe_u32 v213, v9, 16, 1
	v_bfe_u32 v214, v1, 16, 1
	v_bfe_u32 v215, v10, 16, 1
	v_bfe_u32 v216, v2, 16, 1
	v_add3_u32 v204, v204, v210, s75
	v_add3_u32 v0, v0, v212, s75
	v_add3_u32 v8, v8, v211, s75
	v_add3_u32 v9, v9, v213, s75
	v_add3_u32 v1, v1, v214, s75
	v_add3_u32 v10, v10, v215, s75
	global_store_short_d16_hi v[130:131], v204, off offset:128
	global_store_short_d16_hi v[132:133], v8, off offset:128
	global_store_short_d16_hi v[134:135], v0, off offset:128
	global_store_short_d16_hi v[138:139], v9, off offset:128
	global_store_short_d16_hi v[136:137], v1, off offset:128
	global_store_short_d16_hi v[140:141], v10, off offset:128
	v_add3_u32 v0, v2, v216, s75
	global_store_short_d16_hi v[142:143], v0, off offset:128
	v_mul_f32_e32 v0, v194, v11
	v_fmac_f32_e32 v0, v195, v3
	v_bfe_u32 v1, v0, 16, 1
	v_add3_u32 v0, v0, v1, s75
	global_store_short_d16_hi v[144:145], v0, off offset:128
	v_mul_f32_e32 v0, v197, v12
	v_fma_f32 v0, v196, v4, -v0
	v_bfe_u32 v1, v0, 16, 1
	v_add3_u32 v0, v0, v1, s75
	global_store_short_d16_hi v[146:147], v0, off offset:128
	v_mul_f32_e32 v0, v196, v12
	v_fmac_f32_e32 v0, v197, v4
	v_bfe_u32 v1, v0, 16, 1
	v_add3_u32 v0, v0, v1, s75
	global_store_short_d16_hi v[148:149], v0, off offset:128
	v_mul_f32_e32 v0, v199, v13
	v_fma_f32 v0, v198, v5, -v0
	v_bfe_u32 v1, v0, 16, 1
	v_add3_u32 v0, v0, v1, s75
	global_store_short_d16_hi v[150:151], v0, off offset:128
	v_mul_f32_e32 v0, v198, v13
	v_fmac_f32_e32 v0, v199, v5
	v_bfe_u32 v1, v0, 16, 1
	v_add3_u32 v0, v0, v1, s75
	global_store_short_d16_hi v[152:153], v0, off offset:128
	v_mul_f32_e32 v0, v201, v14
	v_fma_f32 v0, v200, v6, -v0
	v_bfe_u32 v1, v0, 16, 1
	v_add3_u32 v0, v0, v1, s75
	global_store_short_d16_hi v[154:155], v0, off offset:128
	v_mul_f32_e32 v0, v200, v14
	v_fmac_f32_e32 v0, v201, v6
	v_bfe_u32 v1, v0, 16, 1
	v_add3_u32 v0, v0, v1, s75
	global_store_short_d16_hi v[156:157], v0, off offset:128
	v_mul_f32_e32 v0, v203, v15
	v_fma_f32 v0, v202, v7, -v0
	v_bfe_u32 v1, v0, 16, 1
	v_add3_u32 v0, v0, v1, s75
	global_store_short_d16_hi v[158:159], v0, off offset:128
	v_mul_f32_e32 v0, v202, v15
	v_fmac_f32_e32 v0, v203, v7
	v_bfe_u32 v1, v0, 16, 1
	v_add3_u32 v0, v0, v1, s75
	global_store_short_d16_hi v[160:161], v0, off offset:128
	ds_read_b64_tr_b16 v[0:1], v162 offset:0x600
	ds_read_b64_tr_b16 v[2:3], v162 offset:0xe00
	ds_read_b64_tr_b16 v[210:211], v162 offset:0x1600
	ds_read_b64_tr_b16 v[212:213], v162 offset:0x1e00
	ds_read_b64_tr_b16 v[214:215], v162 offset:0x2600
	ds_read_b64_tr_b16 v[216:217], v162 offset:0x2e00
	ds_read_b64_tr_b16 v[218:219], v162 offset:0x3600
	ds_read_b64_tr_b16 v[220:221], v162 offset:0x3e00
	s_waitcnt lgkmcnt(0)
	s_nop 0
	v_mfma_f32_32x32x16_bf16 v[0:15], v[76:79], v[0:3], 0
	v_mfma_f32_32x32x16_bf16 v[0:15], v[72:75], v[210:213], v[0:15]
	ds_read_b64_tr_b16 v[210:211], v162 offset:0x4600
	ds_read_b64_tr_b16 v[212:213], v162 offset:0x4e00
	v_mfma_f32_32x32x16_bf16 v[0:15], v[68:71], v[214:217], v[0:15]
	ds_read_b64_tr_b16 v[214:215], v162 offset:0x5600
	ds_read_b64_tr_b16 v[216:217], v162 offset:0x5e00
	v_mfma_f32_32x32x16_bf16 v[0:15], v[64:67], v[218:221], v[0:15]
	ds_read_b64_tr_b16 v[218:219], v162 offset:0x6600
	ds_read_b64_tr_b16 v[220:221], v162 offset:0x6e00
	ds_read_b64_tr_b16 v[222:223], v162 offset:0x7600
	ds_read_b64_tr_b16 v[224:225], v162 offset:0x7e00
	s_waitcnt lgkmcnt(0)
; __device__ __forceinline__ void fourier_step1(Ctx& F, const bf16* P, bf16* Y) {
;     ...
;             F1_D0(0); F1_D0(1); F1_D0(2); F1_D0(3);
;     ...
;             __syncthreads();
;         }
;     }
	v_mfma_f32_32x32x16_bf16 v[0:15], v[60:63], v[210:213], v[0:15]
	ds_read_b64_tr_b16 v[210:211], v162 offset:0x8600
	ds_read_b64_tr_b16 v[212:213], v162 offset:0x8e00
	v_mfma_f32_32x32x16_bf16 v[0:15], v[56:59], v[214:217], v[0:15]
	ds_read_b64_tr_b16 v[214:215], v162 offset:0x9600
	ds_read_b64_tr_b16 v[216:217], v162 offset:0x9e00
	v_mfma_f32_32x32x16_bf16 v[0:15], v[52:55], v[218:221], v[0:15]
	ds_read_b64_tr_b16 v[218:219], v162 offset:0xa600
	ds_read_b64_tr_b16 v[220:221], v162 offset:0xae00
	v_mfma_f32_32x32x16_bf16 v[0:15], v[48:51], v[222:225], v[0:15]
	ds_read_b64_tr_b16 v[222:223], v162 offset:0xb600
	ds_read_b64_tr_b16 v[224:225], v162 offset:0xbe00
	s_waitcnt lgkmcnt(0)
	v_mfma_f32_32x32x16_bf16 v[0:15], v[44:47], v[210:213], v[0:15]
	ds_read_b64_tr_b16 v[210:211], v162 offset:0xc600
	ds_read_b64_tr_b16 v[212:213], v162 offset:0xce00
	v_mfma_f32_32x32x16_bf16 v[0:15], v[40:43], v[214:217], v[0:15]
	ds_read_b64_tr_b16 v[214:215], v162 offset:0xd600
	ds_read_b64_tr_b16 v[216:217], v162 offset:0xde00
	v_mfma_f32_32x32x16_bf16 v[0:15], v[36:39], v[218:221], v[0:15]
	ds_read_b64_tr_b16 v[218:219], v162 offset:0xe600
	ds_read_b64_tr_b16 v[220:221], v162 offset:0xee00
	v_mfma_f32_32x32x16_bf16 v[0:15], v[32:35], v[222:225], v[0:15]
	ds_read_b64_tr_b16 v[222:223], v162 offset:0xf600
	ds_read_b64_tr_b16 v[224:225], v162 offset:0xfe00
	s_waitcnt lgkmcnt(0)
	v_mfma_f32_32x32x16_bf16 v[0:15], v[28:31], v[210:213], v[0:15]
	s_movk_i32 s12, 0x80
	s_and_b64 vcc, exec, s[4:5]
	s_mov_b64 s[4:5], 0
	v_mfma_f32_32x32x16_bf16 v[0:15], v[24:27], v[214:217], v[0:15]
	v_mfma_f32_32x32x16_bf16 v[0:15], v[20:23], v[218:221], v[0:15]
	v_mfma_f32_32x32x16_bf16 v[0:15], v[16:19], v[222:225], v[0:15]
	s_nop 11
	v_mul_f32_e32 v204, v189, v8
	v_mul_f32_e32 v8, v188, v8
	v_fmac_f32_e32 v8, v189, v0
	v_fma_f32 v204, v188, v0, -v204
	v_bfe_u32 v0, v8, 16, 1
	v_add3_u32 v0, v8, v0, s75
	global_store_short_d16_hi v[132:133], v0, off offset:192
	v_mul_f32_e32 v0, v191, v9
	v_fma_f32 v0, v190, v1, -v0
	v_bfe_u32 v8, v0, 16, 1
	v_add3_u32 v0, v0, v8, s75
	global_store_short_d16_hi v[134:135], v0, off offset:192
	v_mul_f32_e32 v0, v190, v9
	v_fmac_f32_e32 v0, v191, v1
	v_bfe_u32 v210, v204, 16, 1
	v_bfe_u32 v1, v0, 16, 1
	v_add3_u32 v204, v204, v210, s75
	v_add3_u32 v0, v0, v1, s75
	global_store_short_d16_hi v[130:131], v204, off offset:192
	global_store_short_d16_hi v[138:139], v0, off offset:192
	v_mul_f32_e32 v0, v193, v10
	v_fma_f32 v0, v192, v2, -v0
	v_bfe_u32 v1, v0, 16, 1
	v_add3_u32 v0, v0, v1, s75
	global_store_short_d16_hi v[136:137], v0, off offset:192
	v_mul_f32_e32 v0, v192, v10
	v_fmac_f32_e32 v0, v193, v2
	v_bfe_u32 v1, v0, 16, 1
	v_add3_u32 v0, v0, v1, s75
	global_store_short_d16_hi v[140:141], v0, off offset:192
	v_mul_f32_e32 v0, v195, v11
	v_fma_f32 v0, v194, v3, -v0
	v_bfe_u32 v1, v0, 16, 1
	v_add3_u32 v0, v0, v1, s75
	global_store_short_d16_hi v[142:143], v0, off offset:192
	v_mul_f32_e32 v0, v194, v11
	v_fmac_f32_e32 v0, v195, v3
	v_bfe_u32 v1, v0, 16, 1
	v_add3_u32 v0, v0, v1, s75
	global_store_short_d16_hi v[144:145], v0, off offset:192
	v_mul_f32_e32 v0, v197, v12
	v_fma_f32 v0, v196, v4, -v0
	v_bfe_u32 v1, v0, 16, 1
	v_add3_u32 v0, v0, v1, s75
	global_store_short_d16_hi v[146:147], v0, off offset:192
	v_mul_f32_e32 v0, v196, v12
	v_fmac_f32_e32 v0, v197, v4
	v_bfe_u32 v1, v0, 16, 1
	v_add3_u32 v0, v0, v1, s75
	global_store_short_d16_hi v[148:149], v0, off offset:192
	v_mul_f32_e32 v0, v199, v13
	v_fma_f32 v0, v198, v5, -v0
	v_bfe_u32 v1, v0, 16, 1
	v_add3_u32 v0, v0, v1, s75
	global_store_short_d16_hi v[150:151], v0, off offset:192
	v_mul_f32_e32 v0, v198, v13
	v_fmac_f32_e32 v0, v199, v5
	v_bfe_u32 v1, v0, 16, 1
	v_add3_u32 v0, v0, v1, s75
	global_store_short_d16_hi v[152:153], v0, off offset:192
	v_mul_f32_e32 v0, v201, v14
	v_fma_f32 v0, v200, v6, -v0
	v_bfe_u32 v1, v0, 16, 1
	v_add3_u32 v0, v0, v1, s75
	global_store_short_d16_hi v[154:155], v0, off offset:192
	v_mul_f32_e32 v0, v200, v14
	v_fmac_f32_e32 v0, v201, v6
	v_bfe_u32 v1, v0, 16, 1
	v_add3_u32 v0, v0, v1, s75
	global_store_short_d16_hi v[156:157], v0, off offset:192
	v_mul_f32_e32 v0, v203, v15
	v_fma_f32 v0, v202, v7, -v0
	v_bfe_u32 v1, v0, 16, 1
	v_add3_u32 v0, v0, v1, s75
	global_store_short_d16_hi v[158:159], v0, off offset:192
	v_mul_f32_e32 v0, v202, v15
	v_fmac_f32_e32 v0, v203, v7
	v_bfe_u32 v1, v0, 16, 1
	v_add3_u32 v0, v0, v1, s75
	global_store_short_d16_hi v[160:161], v0, off offset:192
	s_waitcnt vmcnt(63) expcnt(7) lgkmcnt(15)
	s_barrier
	s_cbranch_vccnz .LBB0_510
	s_add_i32 s8, s8, s89
	s_cmpk_lt_i32 s8, 0x100
	s_cbranch_scc1 .LBB0_509
	v_readlane_b32 s76, v255, 37
